# phase 0 rmsnorm row loop: norm weights hoisted into registers (no per-row reloads and store-ack waits), next row's x loads prefetched one iteration ahead
# speedup vs baseline: 1.0032x; 1.0032x over previous
; DI int opaque_tid() { int t = threadIdx.x; asm volatile("" : "+v"(t)); return t; }
; DI void phase_prep(const Params& p, char* smem) {
;     ...
;     const int lane = threadIdx.x & 63, wid = threadIdx.x >> 6;
;     float* wT = (float*)smem;
;     for (int i = opaque_tid(); i < 2048; i += 256) {
;       const int k = i >> 1, hf = i & 1;
;       float4 w = *(const float4*)(p.w_in_even + (size_t)k * EIN + EINP + hf * 4);
;       wT[(hf * 4 + 0) * 1024 + k] = w.x; wT[(hf * 4 + 1) * 1024 + k] = w.y;
;       wT[(hf * 4 + 2) * 1024 + k] = w.z; wT[(hf * 4 + 3) * 1024 + k] = w.w;
;     }
;     __syncthreads();
;     for (int row = blockIdx.x * 4 + wid; row < NROW; row += gridDim.x * 4) {
;       const float* xr = row < NPR ? p.x_prompt + (size_t)row * DM : p.x_sample + (size_t)(row - NPR) * DM;
;       float4 v[4];
;       float ss = 0.f;
; #pragma unroll
;       for (int j = 0; j < 4; ++j) {
;         v[j] = ((const float4*)xr)[j * 64 + lane];
;         ss += v[j].x * v[j].x + v[j].y * v[j].y + v[j].z * v[j].z + v[j].w * v[j].w;
;       }
;       ss = wave_sum(ss);
;       float inv = rsqrtf(ss * (1.0f / 1024.0f) + EPSF);
.LBB0_48:
	s_or_b64 exec, exec, s[0:1]
	v_lshrrev_b32_e32 v0, 6, v196
	v_lshl_add_u32 v140, s46, 2, v0
	s_movk_i32 s0, 0x4080
	v_cmp_gt_i32_e32 vcc, s0, v140
	s_waitcnt lgkmcnt(0)
	s_barrier
	s_and_saveexec_b64 s[2:3], vcc
	s_cbranch_execz .LBB0_57
	s_load_dwordx2 s[10:11], s[92:93], 0x148
	s_load_dwordx4 s[4:7], s[92:93], 0x0
	v_and_b32_e32 v128, 63, v196
	v_mov_b32_e32 v143, 0
	v_lshlrev_b32_e32 v142, 4, v128
	v_lshlrev_b32_e32 v0, 3, v128
	v_mov_b32_e32 v1, v143
	s_waitcnt lgkmcnt(0)
	v_lshl_add_u64 v[146:147], s[10:11], 0, v[0:1]
	ds_read_b128 v[0:3], v142
	ds_read_b128 v[4:7], v142 offset:1024
	ds_read_b128 v[8:11], v142 offset:4096
	ds_read_b128 v[12:15], v142 offset:5120
	ds_read_b128 v[16:19], v142 offset:8192
	ds_read_b128 v[20:23], v142 offset:9216
	ds_read_b128 v[24:27], v142 offset:12288
	ds_read_b128 v[28:31], v142 offset:13312
	ds_read_b128 v[32:35], v142 offset:16384
	ds_read_b128 v[36:39], v142 offset:17408
	ds_read_b128 v[40:43], v142 offset:20480
	ds_read_b128 v[44:47], v142 offset:21504
	ds_read_b128 v[48:51], v142 offset:24576
	ds_read_b128 v[52:55], v142 offset:25600
	ds_read_b128 v[56:59], v142 offset:28672
	ds_read_b128 v[60:63], v142 offset:29696
	ds_read_b128 v[64:67], v142 offset:2048
	ds_read_b128 v[68:71], v142 offset:3072
	ds_read_b128 v[72:75], v142 offset:6144
	ds_read_b128 v[76:79], v142 offset:7168
	ds_read_b128 v[80:83], v142 offset:10240
	ds_read_b128 v[84:87], v142 offset:11264
	ds_read_b128 v[88:91], v142 offset:14336
	ds_read_b128 v[92:95], v142 offset:15360
	ds_read_b128 v[96:99], v142 offset:18432
	ds_read_b128 v[100:103], v142 offset:19456
	ds_read_b128 v[104:107], v142 offset:22528
	ds_read_b128 v[108:111], v142 offset:23552
	ds_read_b128 v[112:115], v142 offset:26624
	ds_read_b128 v[116:119], v142 offset:27648
	ds_read_b128 v[120:123], v142 offset:30720
	ds_read_b128 v[124:127], v142 offset:31744
	s_load_dwordx2 s[0:1], s[92:93], 0x48
	s_load_dwordx2 s[8:9], s[92:93], 0x110
	v_cmp_eq_u32_e32 vcc, 0, v128
	s_lshl_b32 s12, s34, 2
	s_mov_b64 s[10:11], 0
	s_waitcnt lgkmcnt(0)
	v_lshl_add_u64 v[144:145], s[0:1], 0, v[142:143]
	s_movk_i32 s13, 0x3fff
	v_lshlrev_b32_e32 v148, 4, v128
	v_mov_b32_e32 v160, 0x358637bd
	s_mov_b32 s14, 0x800000
	s_movk_i32 s15, 0x407f
	v_mov_b32_e32 v149, v143
	v_mov_b32_e32 v161, 0x3a800000
	global_load_dwordx4 v[200:203], v[144:145], off
	global_load_dwordx4 v[204:207], v[144:145], off offset:1024
	global_load_dwordx4 v[208:211], v[144:145], off offset:2048
	global_load_dwordx4 v[212:215], v[144:145], off offset:3072
	v_readfirstlane_b32 s98, v140
	s_sub_u32 s99, s98, 0x4000
	s_cmp_gt_i32 s98, 0x3fff
	s_cselect_b32 s99, s99, s98
	s_cselect_b32 s100, s6, s4
	s_cselect_b32 s101, s7, s5
	s_lshr_b32 s98, s99, 20
	s_lshl_b32 s99, s99, 12
	s_add_u32 s100, s100, s99
	s_addc_u32 s101, s101, s98
	global_load_dwordx4 v[216:219], v148, s[100:101]
	global_load_dwordx4 v[220:223], v148, s[100:101] offset:1024
	global_load_dwordx4 v[224:227], v148, s[100:101] offset:2048
	global_load_dwordx4 v[228:231], v148, s[100:101] offset:3072
	s_branch .LBB0_51

; DI void phase_prep(const Params& p, char* smem) {
;     ...
;     for (int row = blockIdx.x * 4 + wid; row < NROW; row += gridDim.x * 4) {
;       const float* xr = row < NPR ? p.x_prompt + (size_t)row * DM : p.x_sample + (size_t)(row - NPR) * DM;
;       float4 v[4];
;       float ss = 0.f;
; #pragma unroll
;       for (int j = 0; j < 4; ++j) {
;         v[j] = ((const float4*)xr)[j * 64 + lane];
;         ss += v[j].x * v[j].x + v[j].y * v[j].y + v[j].z * v[j].z + v[j].w * v[j].w;
;       }
;       ss = wave_sum(ss);
;       float inv = rsqrtf(ss * (1.0f / 1024.0f) + EPSF);
;       float part[8];
; #pragma unroll
;       for (int c = 0; c < 8; ++c) part[c] = 0.f;
; #pragma unroll
;       for (int j = 0; j < 4; ++j) {
;         float4 g = ((const float4*)p.norm_mix)[j * 64 + lane];
;         uint2 o;
;         const float h0 = v[j].x * inv * g.x, h1 = v[j].y * inv * g.y, h2 = v[j].z * inv * g.z, h3 = v[j].w * inv * g.w;
.LBB0_51:
	s_waitcnt vmcnt(0)
	v_mov_b32_e32 v136, v216
	v_mov_b32_e32 v137, v217
	v_mov_b32_e32 v138, v218
	v_mov_b32_e32 v139, v219
	v_mov_b32_e32 v156, v220
	v_mov_b32_e32 v157, v221
	v_mov_b32_e32 v158, v222
	v_mov_b32_e32 v159, v223
	v_mov_b32_e32 v128, v224
	v_mov_b32_e32 v129, v225
	v_mov_b32_e32 v130, v226
	v_mov_b32_e32 v131, v227
	v_mov_b32_e32 v132, v228
	v_mov_b32_e32 v133, v229
	v_mov_b32_e32 v134, v230
	v_mov_b32_e32 v135, v231
	v_mov_b32_e32 v141, 0
	v_add_u32_e32 v232, s12, v140
	s_nop 1
	v_readfirstlane_b32 s98, v232
	s_nop 1
	s_cmp_gt_i32 s98, 0x407f
	s_cbranch_scc1 .Lprep_nopf
	s_sub_u32 s99, s98, 0x4000
	s_cmp_gt_i32 s98, 0x3fff
	s_cselect_b32 s99, s99, s98
	s_cselect_b32 s100, s6, s4
	s_cselect_b32 s101, s7, s5
	s_lshr_b32 s98, s99, 20
	s_lshl_b32 s99, s99, 12
	s_add_u32 s100, s100, s99
	s_addc_u32 s101, s101, s98
	global_load_dwordx4 v[216:219], v148, s[100:101]
	global_load_dwordx4 v[220:223], v148, s[100:101] offset:1024
	global_load_dwordx4 v[224:227], v148, s[100:101] offset:2048
	global_load_dwordx4 v[228:231], v148, s[100:101] offset:3072
.Lprep_nopf:
	v_mov_b32_e32 v162, v200
	v_mov_b32_e32 v163, v201
	v_mov_b32_e32 v164, v202
	v_mov_b32_e32 v165, v203
	v_mov_b32_e32 v142, 0
	v_mov_b32_e32 v176, 0
	v_mov_b32_e32 v177, 0
	v_mov_b32_e32 v166, v137
	v_mov_b32_e32 v167, v157
	v_mov_b32_e32 v154, v136
	v_mov_b32_e32 v155, v156
	v_mov_b32_e32 v174, v129
	v_mov_b32_e32 v175, v133
	v_pk_mul_f32 v[166:167], v[166:167], v[166:167]
	v_mov_b32_e32 v150, v138
	v_mov_b32_e32 v151, v158
	v_mov_b32_e32 v172, v128
	v_mov_b32_e32 v173, v132
	v_pk_mul_f32 v[174:175], v[174:175], v[174:175]
	v_pk_fma_f32 v[154:155], v[154:155], v[154:155], v[166:167]
	v_mov_b32_e32 v152, v139
	v_mov_b32_e32 v153, v159
	v_mov_b32_e32 v168, v130
	v_mov_b32_e32 v169, v134
	v_pk_fma_f32 v[166:167], v[172:173], v[172:173], v[174:175]
	v_pk_fma_f32 v[150:151], v[150:151], v[150:151], v[154:155]
	v_mov_b32_e32 v170, v131
	v_mov_b32_e32 v171, v135
	v_pk_fma_f32 v[154:155], v[168:169], v[168:169], v[166:167]
	v_pk_fma_f32 v[150:151], v[152:153], v[152:153], v[150:151]
	v_pk_fma_f32 v[152:153], v[170:171], v[170:171], v[154:155]
	v_add_f32_e32 v150, v150, v151
	v_add_f32_e32 v150, v150, v152
	v_add_f32_e32 v150, v150, v153
	v_mov_b32_e32 v166, 0
	v_mov_b32_e32 v168, 0
	v_add_f32_dpp v150, v150, v150 quad_perm:[1,0,3,2] row_mask:0xf bank_mask:0xf bound_ctrl:1
	v_mov_b32_e32 v170, 0
	v_mov_b32_e32 v172, 0
	v_add_f32_dpp v150, v150, v150 quad_perm:[2,3,0,1] row_mask:0xf bank_mask:0xf bound_ctrl:1
	v_mov_b32_e32 v174, 0
	v_mov_b32_e32 v167, 0
	v_add_f32_dpp v150, v150, v150 row_half_mirror row_mask:0xf bank_mask:0xf bound_ctrl:1
	v_mov_b32_e32 v169, 0
	v_mov_b32_e32 v171, 0
	v_add_f32_dpp v150, v150, v150 row_mirror row_mask:0xf bank_mask:0xf bound_ctrl:1
	v_mov_b32_e32 v173, 0
	v_mov_b32_e32 v175, 0
	v_mov_b32_dpp v142, v150 row_bcast:15 row_mask:0xa bank_mask:0xf
	v_add_f32_e32 v142, v150, v142
	s_nop 1
	v_mov_b32_dpp v176, v142 row_bcast:31 row_mask:0xc bank_mask:0xf
	v_add_f32_e32 v142, v142, v176
	v_mov_b32_e32 v176, 0
	v_readlane_b32 s0, v142, 63
	s_nop 1
	v_fma_f32 v142, s0, v161, v160
	v_mul_f32_e32 v150, 0x4b800000, v142
	v_cmp_gt_f32_e64 s[0:1], s14, v142
	s_nop 1
	v_cndmask_b32_e64 v142, v142, v150, s[0:1]
	v_rsq_f32_e32 v142, v142
	v_lshlrev_b64 v[150:151], 11, v[140:141]
	v_lshl_add_u64 v[150:151], v[146:147], 0, v[150:151]
	v_mul_f32_e32 v152, 0x45800000, v142
	v_cndmask_b32_e64 v142, v142, v152, s[0:1]
	v_pk_mul_f32 v[136:137], v[136:137], v[142:143] op_sel_hi:[1,0]
	v_pk_mul_f32 v[138:139], v[138:139], v[142:143] op_sel_hi:[1,0]
	v_pk_mul_f32 v[154:155], v[162:163], v[136:137]
	v_pk_mul_f32 v[152:153], v[164:165], v[138:139]
	v_cvt_pk_bf16_f32 v136, v154, v155
	v_cvt_pk_bf16_f32 v137, v152, v153
	global_store_dwordx2 v[150:151], v[136:137], off
	s_nop 1
	v_mov_b32_e32 v136, v204
	v_mov_b32_e32 v137, v205
	v_mov_b32_e32 v138, v206
	v_mov_b32_e32 v139, v207
	v_pk_mul_f32 v[156:157], v[156:157], v[142:143] op_sel_hi:[1,0]
	v_pk_mul_f32 v[162:163], v[158:159], v[142:143] op_sel_hi:[1,0]
	v_pk_mul_f32 v[128:129], v[128:129], v[142:143] op_sel_hi:[1,0]
	v_pk_mul_f32 v[130:131], v[130:131], v[142:143] op_sel_hi:[1,0]
	v_mul_f32_e32 v178, v155, v9
	v_mul_f32_e32 v179, v155, v17
	v_mul_f32_e32 v180, v155, v25
	v_mul_f32_e32 v181, v155, v33
	v_mul_f32_e32 v182, v155, v41
	v_mul_f32_e32 v183, v155, v49
	v_pk_mul_f32 v[132:133], v[132:133], v[142:143] op_sel_hi:[1,0]
	v_pk_mul_f32 v[134:135], v[134:135], v[142:143] op_sel_hi:[1,0]
	v_mul_f32_e32 v142, v155, v1
	v_mul_f32_e32 v155, v155, v57
	v_fmac_f32_e32 v178, v154, v8
	v_fmac_f32_e32 v179, v154, v16
	v_fmac_f32_e32 v180, v154, v24
	v_fmac_f32_e32 v181, v154, v32
	v_fmac_f32_e32 v182, v154, v40
	v_fmac_f32_e32 v183, v154, v48
	v_fmac_f32_e32 v142, v154, v0
	v_fmac_f32_e32 v155, v154, v56
	v_fmac_f32_e32 v178, v152, v10
	v_fmac_f32_e32 v179, v152, v18
	v_fmac_f32_e32 v180, v152, v26
	v_fmac_f32_e32 v181, v152, v34
	v_fmac_f32_e32 v182, v152, v42
	v_fmac_f32_e32 v183, v152, v50
	v_fmac_f32_e32 v142, v152, v2
	v_fmac_f32_e32 v155, v152, v58
	v_fmac_f32_e32 v178, v153, v11
	v_fmac_f32_e32 v179, v153, v19
	v_fmac_f32_e32 v180, v153, v27
	v_fmac_f32_e32 v181, v153, v35
	v_fmac_f32_e32 v182, v153, v43
	v_fmac_f32_e32 v183, v153, v51
	v_fmac_f32_e32 v142, v153, v3
	v_fmac_f32_e32 v155, v153, v59
	v_add_f32_e32 v152, 0, v178
	v_add_f32_e32 v153, 0, v179
	v_add_f32_e32 v154, 0, v180
	v_add_f32_e32 v178, 0, v181
	v_add_f32_e32 v179, 0, v182
	v_add_f32_e32 v180, 0, v183
	v_add_f32_e32 v142, 0, v142
	v_add_f32_e32 v155, 0, v155
	v_mov_b32_e32 v164, 0
	v_mov_b32_e32 v165, 0
	v_pk_mul_f32 v[158:159], v[156:157], v[136:137]
; DI void phase_prep(const Params& p, char* smem) {
;     ...
;       for (int j = 0; j < 4; ++j) {
;         float4 g = ((const float4*)p.norm_mix)[j * 64 + lane];
;         uint2 o;
;         const float h0 = v[j].x * inv * g.x, h1 = v[j].y * inv * g.y, h2 = v[j].z * inv * g.z, h3 = v[j].w * inv * g.w;
;         o.x = pack2(h0, h1);
;         o.y = pack2(h2, h3);
;         ((uint2*)(p.H + (size_t)row * DM))[j * 64 + lane] = o;
; #pragma unroll
;         for (int c = 0; c < 8; ++c) {
;           float4 w = ((const float4*)(wT + c * 1024))[j * 64 + lane];
;           part[c] += h0 * w.x + h1 * w.y + h2 * w.z + h3 * w.w;
;         }
;       }
	v_pk_mul_f32 v[156:157], v[162:163], v[138:139]
	v_cvt_pk_bf16_f32 v136, v158, v159
	v_cvt_pk_bf16_f32 v137, v156, v157
	global_store_dwordx2 v[150:151], v[136:137], off offset:512
	s_nop 1
	v_mov_b32_e32 v136, v208
	v_mov_b32_e32 v137, v209
	v_mov_b32_e32 v138, v210
	v_mov_b32_e32 v139, v211
	v_mul_f32_e32 v181, v159, v5
	v_mul_f32_e32 v182, v159, v13
	v_mul_f32_e32 v183, v159, v21
	v_mul_f32_e32 v184, v159, v29
	v_mul_f32_e32 v185, v159, v37
	v_mul_f32_e32 v186, v159, v45
	v_mul_f32_e32 v187, v159, v53
	v_mul_f32_e32 v159, v159, v61
	v_fmac_f32_e32 v181, v158, v4
	v_fmac_f32_e32 v182, v158, v12
	v_fmac_f32_e32 v183, v158, v20
	v_fmac_f32_e32 v185, v158, v36
	v_fmac_f32_e32 v186, v158, v44
	v_fmac_f32_e32 v187, v158, v52
	v_fmac_f32_e32 v159, v158, v60
	v_fmac_f32_e32 v184, v158, v28
	v_fmac_f32_e32 v181, v156, v6
	v_fmac_f32_e32 v182, v156, v14
	v_fmac_f32_e32 v183, v156, v22
	v_fmac_f32_e32 v185, v156, v38
	v_fmac_f32_e32 v186, v156, v46
	v_fmac_f32_e32 v187, v156, v54
	v_fmac_f32_e32 v159, v156, v62
	v_fmac_f32_e32 v184, v156, v30
	v_fmac_f32_e32 v181, v157, v7
	v_fmac_f32_e32 v182, v157, v15
	v_fmac_f32_e32 v183, v157, v23
	v_fmac_f32_e32 v185, v157, v39
	v_fmac_f32_e32 v186, v157, v47
	v_fmac_f32_e32 v187, v157, v55
	v_fmac_f32_e32 v159, v157, v63
	v_fmac_f32_e32 v184, v157, v31
	v_add_f32_e32 v142, v142, v181
	v_add_f32_e32 v152, v152, v182
	v_add_f32_e32 v153, v153, v183
	v_add_f32_e32 v156, v178, v185
	v_add_f32_e32 v157, v179, v186
	v_add_f32_e32 v158, v180, v187
	v_add_f32_e32 v155, v155, v159
	v_add_f32_e32 v154, v154, v184
	v_mov_b32_e32 v162, 0
	v_mov_b32_e32 v163, 0
	v_pk_mul_f32 v[136:137], v[128:129], v[136:137]
	v_pk_mul_f32 v[138:139], v[130:131], v[138:139]
	v_cvt_pk_bf16_f32 v128, v136, v137
	v_cvt_pk_bf16_f32 v129, v138, v139
	global_store_dwordx2 v[150:151], v[128:129], off offset:1024
	s_nop 1
	v_mov_b32_e32 v128, v212
	v_mov_b32_e32 v129, v213
	v_mov_b32_e32 v130, v214
	v_mov_b32_e32 v131, v215
	v_mul_f32_e32 v159, v137, v65
	v_mul_f32_e32 v178, v137, v73
	v_mul_f32_e32 v179, v137, v81
	v_mul_f32_e32 v180, v137, v89
	v_mul_f32_e32 v181, v137, v97
	v_mul_f32_e32 v182, v137, v105
	v_mul_f32_e32 v183, v137, v113
	v_mul_f32_e32 v137, v137, v121
	v_fmac_f32_e32 v159, v136, v64
	v_fmac_f32_e32 v178, v136, v72
	v_fmac_f32_e32 v179, v136, v80
	v_fmac_f32_e32 v180, v136, v88
	v_fmac_f32_e32 v181, v136, v96
	v_fmac_f32_e32 v182, v136, v104
	v_fmac_f32_e32 v183, v136, v112
	v_fmac_f32_e32 v137, v136, v120
	v_fmac_f32_e32 v159, v138, v66
	v_fmac_f32_e32 v178, v138, v74
	v_fmac_f32_e32 v179, v138, v82
	v_fmac_f32_e32 v180, v138, v90
	v_fmac_f32_e32 v181, v138, v98
	v_fmac_f32_e32 v182, v138, v106
	v_fmac_f32_e32 v183, v138, v114
	v_fmac_f32_e32 v137, v138, v122
	v_fmac_f32_e32 v159, v139, v67
	v_fmac_f32_e32 v178, v139, v75
	v_fmac_f32_e32 v179, v139, v83
	v_fmac_f32_e32 v180, v139, v91
	v_fmac_f32_e32 v181, v139, v99
	v_fmac_f32_e32 v182, v139, v107
	v_fmac_f32_e32 v183, v139, v115
	v_fmac_f32_e32 v137, v139, v123
	v_add_f32_e32 v136, v142, v159
	v_add_f32_e32 v138, v152, v178
	v_add_f32_e32 v139, v153, v179
	v_add_f32_e32 v142, v154, v180
	v_add_f32_e32 v152, v156, v181
	v_add_f32_e32 v153, v157, v182
	v_add_f32_e32 v154, v158, v183
	v_add_f32_e32 v137, v155, v137
	v_pk_mul_f32 v[128:129], v[132:133], v[128:129]
	v_pk_mul_f32 v[130:131], v[134:135], v[130:131]
	v_cvt_pk_bf16_f32 v132, v128, v129
	v_mul_f32_e32 v134, v129, v69
	v_mul_f32_e32 v135, v129, v77
	v_mul_f32_e32 v155, v129, v85
	v_mul_f32_e32 v156, v129, v93
	v_mul_f32_e32 v157, v129, v101
	v_mul_f32_e32 v158, v129, v109
	v_mul_f32_e32 v159, v129, v117
	v_mul_f32_e32 v129, v129, v125
	v_fmac_f32_e32 v134, v128, v68
	v_fmac_f32_e32 v135, v128, v76
	v_fmac_f32_e32 v155, v128, v84
	v_fmac_f32_e32 v156, v128, v92
	v_fmac_f32_e32 v157, v128, v100
	v_fmac_f32_e32 v158, v128, v108
	v_fmac_f32_e32 v159, v128, v116
	v_fmac_f32_e32 v129, v128, v124
	v_fmac_f32_e32 v134, v130, v70
	v_fmac_f32_e32 v135, v130, v78
	v_fmac_f32_e32 v155, v130, v86
	v_fmac_f32_e32 v156, v130, v94
	v_fmac_f32_e32 v157, v130, v102
	v_fmac_f32_e32 v158, v130, v110
	v_fmac_f32_e32 v159, v130, v118
	v_fmac_f32_e32 v129, v130, v126
	v_cvt_pk_bf16_f32 v133, v130, v131
	v_fmac_f32_e32 v134, v131, v71
	v_fmac_f32_e32 v135, v131, v79
	v_fmac_f32_e32 v155, v131, v87
	v_fmac_f32_e32 v156, v131, v95
	v_fmac_f32_e32 v157, v131, v103
	v_fmac_f32_e32 v158, v131, v111
	v_fmac_f32_e32 v159, v131, v119
	v_fmac_f32_e32 v129, v131, v127
	global_store_dwordx2 v[150:151], v[132:133], off offset:1536
	v_add_f32_e32 v128, v136, v134
	v_add_f32_e32 v130, v138, v135
	v_add_f32_e32 v131, v139, v155
	v_add_f32_e32 v132, v142, v156
	v_add_f32_e32 v133, v152, v157
	v_add_f32_e32 v134, v153, v158
	v_add_f32_e32 v135, v154, v159
	v_add_f32_e32 v129, v137, v129
	v_add_f32_dpp v128, v128, v128 quad_perm:[1,0,3,2] row_mask:0xf bank_mask:0xf bound_ctrl:1
	v_add_f32_dpp v130, v130, v130 quad_perm:[1,0,3,2] row_mask:0xf bank_mask:0xf bound_ctrl:1
; DI void phase_prep(const Params& p, char* smem) {
;     ...
; #pragma unroll
;       for (int c = 0; c < 8; ++c) part[c] = wave_sum(part[c]);
;       if (lane == 0) {
;         float4 a = {part[0], part[1], part[2], part[3]}, b = {part[4], part[5], part[6], part[7]};
;         ((float4*)(p.BGR + (size_t)row * 8))[0] = a;
;         ((float4*)(p.BGR + (size_t)row * 8))[1] = b;
;       }
	v_add_f32_dpp v131, v131, v131 quad_perm:[1,0,3,2] row_mask:0xf bank_mask:0xf bound_ctrl:1
	v_add_f32_dpp v132, v132, v132 quad_perm:[1,0,3,2] row_mask:0xf bank_mask:0xf bound_ctrl:1
	v_add_f32_dpp v133, v133, v133 quad_perm:[1,0,3,2] row_mask:0xf bank_mask:0xf bound_ctrl:1
	v_add_f32_dpp v134, v134, v134 quad_perm:[1,0,3,2] row_mask:0xf bank_mask:0xf bound_ctrl:1
	v_add_f32_dpp v135, v135, v135 quad_perm:[1,0,3,2] row_mask:0xf bank_mask:0xf bound_ctrl:1
	v_add_f32_dpp v129, v129, v129 quad_perm:[1,0,3,2] row_mask:0xf bank_mask:0xf bound_ctrl:1
	v_add_f32_dpp v128, v128, v128 quad_perm:[2,3,0,1] row_mask:0xf bank_mask:0xf bound_ctrl:1
	v_add_f32_dpp v130, v130, v130 quad_perm:[2,3,0,1] row_mask:0xf bank_mask:0xf bound_ctrl:1
	v_add_f32_dpp v131, v131, v131 quad_perm:[2,3,0,1] row_mask:0xf bank_mask:0xf bound_ctrl:1
	v_add_f32_dpp v132, v132, v132 quad_perm:[2,3,0,1] row_mask:0xf bank_mask:0xf bound_ctrl:1
	v_add_f32_dpp v133, v133, v133 quad_perm:[2,3,0,1] row_mask:0xf bank_mask:0xf bound_ctrl:1
	v_add_f32_dpp v134, v134, v134 quad_perm:[2,3,0,1] row_mask:0xf bank_mask:0xf bound_ctrl:1
	v_add_f32_dpp v135, v135, v135 quad_perm:[2,3,0,1] row_mask:0xf bank_mask:0xf bound_ctrl:1
	v_add_f32_dpp v129, v129, v129 quad_perm:[2,3,0,1] row_mask:0xf bank_mask:0xf bound_ctrl:1
	v_add_f32_dpp v128, v128, v128 row_half_mirror row_mask:0xf bank_mask:0xf bound_ctrl:1
	v_add_f32_dpp v130, v130, v130 row_half_mirror row_mask:0xf bank_mask:0xf bound_ctrl:1
	v_add_f32_dpp v131, v131, v131 row_half_mirror row_mask:0xf bank_mask:0xf bound_ctrl:1
	v_add_f32_dpp v132, v132, v132 row_half_mirror row_mask:0xf bank_mask:0xf bound_ctrl:1
	v_add_f32_dpp v133, v133, v133 row_half_mirror row_mask:0xf bank_mask:0xf bound_ctrl:1
	v_add_f32_dpp v134, v134, v134 row_half_mirror row_mask:0xf bank_mask:0xf bound_ctrl:1
	v_add_f32_dpp v135, v135, v135 row_half_mirror row_mask:0xf bank_mask:0xf bound_ctrl:1
	v_add_f32_dpp v129, v129, v129 row_half_mirror row_mask:0xf bank_mask:0xf bound_ctrl:1
	v_add_f32_dpp v128, v128, v128 row_mirror row_mask:0xf bank_mask:0xf bound_ctrl:1
	v_add_f32_dpp v130, v130, v130 row_mirror row_mask:0xf bank_mask:0xf bound_ctrl:1
	v_add_f32_dpp v131, v131, v131 row_mirror row_mask:0xf bank_mask:0xf bound_ctrl:1
	v_add_f32_dpp v132, v132, v132 row_mirror row_mask:0xf bank_mask:0xf bound_ctrl:1
	v_add_f32_dpp v133, v133, v133 row_mirror row_mask:0xf bank_mask:0xf bound_ctrl:1
	v_add_f32_dpp v134, v134, v134 row_mirror row_mask:0xf bank_mask:0xf bound_ctrl:1
	v_add_f32_dpp v135, v135, v135 row_mirror row_mask:0xf bank_mask:0xf bound_ctrl:1
	v_add_f32_dpp v129, v129, v129 row_mirror row_mask:0xf bank_mask:0xf bound_ctrl:1
	v_mov_b32_dpp v162, v128 row_bcast:15 row_mask:0xa bank_mask:0xf
	v_mov_b32_dpp v164, v130 row_bcast:15 row_mask:0xa bank_mask:0xf
	v_mov_b32_dpp v166, v131 row_bcast:15 row_mask:0xa bank_mask:0xf
	v_mov_b32_dpp v168, v132 row_bcast:15 row_mask:0xa bank_mask:0xf
	v_mov_b32_dpp v170, v133 row_bcast:15 row_mask:0xa bank_mask:0xf
	v_mov_b32_dpp v172, v134 row_bcast:15 row_mask:0xa bank_mask:0xf
	v_mov_b32_dpp v174, v135 row_bcast:15 row_mask:0xa bank_mask:0xf
	v_mov_b32_dpp v176, v129 row_bcast:15 row_mask:0xa bank_mask:0xf
	v_add_f32_e32 v128, v128, v162
	v_add_f32_e32 v130, v130, v164
	v_add_f32_e32 v131, v131, v166
	v_add_f32_e32 v132, v132, v168
	v_add_f32_e32 v133, v133, v170
	v_add_f32_e32 v134, v134, v172
	v_add_f32_e32 v135, v135, v174
	v_add_f32_e32 v129, v129, v176
	v_mov_b32_dpp v163, v128 row_bcast:31 row_mask:0xc bank_mask:0xf
	v_mov_b32_dpp v165, v130 row_bcast:31 row_mask:0xc bank_mask:0xf
	v_mov_b32_dpp v167, v131 row_bcast:31 row_mask:0xc bank_mask:0xf
	v_mov_b32_dpp v169, v132 row_bcast:31 row_mask:0xc bank_mask:0xf
	v_mov_b32_dpp v171, v133 row_bcast:31 row_mask:0xc bank_mask:0xf
	v_mov_b32_dpp v173, v134 row_bcast:31 row_mask:0xc bank_mask:0xf
	v_mov_b32_dpp v175, v135 row_bcast:31 row_mask:0xc bank_mask:0xf
	v_mov_b32_dpp v177, v129 row_bcast:31 row_mask:0xc bank_mask:0xf
	v_add_f32_e32 v128, v128, v163
	v_add_f32_e32 v130, v130, v165
	v_add_f32_e32 v131, v131, v167
	v_add_f32_e32 v132, v132, v169
	v_add_f32_e32 v133, v133, v171
	v_add_f32_e32 v134, v134, v173
	v_add_f32_e32 v135, v135, v175
	v_add_f32_e32 v129, v129, v177
	v_readlane_b32 s20, v128, 63
	v_readlane_b32 s21, v130, 63
	v_readlane_b32 s22, v131, 63
	v_readlane_b32 s23, v132, 63
	v_readlane_b32 s16, v133, 63
	v_readlane_b32 s17, v134, 63
	v_readlane_b32 s18, v135, 63
	v_readlane_b32 s19, v129, 63
	s_and_saveexec_b64 s[0:1], vcc
	s_cbranch_execz .LBB0_50
	v_lshlrev_b64 v[128:129], 5, v[140:141]
	v_lshl_add_u64 v[132:133], s[8:9], 0, v[128:129]
	v_mov_b32_e32 v128, s20
	v_mov_b32_e32 v129, s21
	v_mov_b32_e32 v130, s22
	v_mov_b32_e32 v131, s23
	global_store_dwordx4 v[132:133], v[128:131], off
	s_nop 1
	v_mov_b32_e32 v128, s16
	v_mov_b32_e32 v129, s17
	v_mov_b32_e32 v130, s18
	v_mov_b32_e32 v131, s19
	global_store_dwordx4 v[132:133], v[128:131], off offset:16
	s_branch .LBB0_50
